# v78 + adaLN GEMV items spread over all workgroups (wave,wg)=(item/256,item%256) instead of the first 48 virtual CUs on two XCDs
# speedup vs baseline: 1.0127x; 1.0030x over previous
.LBB0_7:
	s_or_b64 exec, exec, s[4:5]
	s_load_dwordx16 s[36:51], s[0:1], 0x0
	s_load_dword s2, s[0:1], 0xd0
	s_load_dwordx2 s[8:9], s[0:1], 0xd8
	s_add_u32 s4, s22, 0x80000
	s_addc_u32 s5, s23, 0
	s_lshr_b32 s26, s73, 6
	s_lshl_b32 s3, s77, 3
	s_add_i32 s79, s3, s26
	s_waitcnt lgkmcnt(0)
	s_lshl_b32 s27, s8, 3
	s_lshl_b32 s98, s26, 8
	s_add_i32 s98, s98, s72
	s_cmpk_gt_i32 s98, 0x17f
	v_mbcnt_lo_u32_b32 v196, -1, 0
	s_cbranch_scc1 .LBB0_14
	s_add_u32 s8, s40, 0x15000
	s_addc_u32 s9, s41, 0
	s_movk_i32 s3, 0x3000
	s_mov_b32 s18, 0xfffeb000
	s_mov_b64 s[10:11], 0x1000
	s_mov_b64 s[12:13], 0x2000
	s_movk_i32 s19, 0x2000
	s_mov_b64 s[14:15], 0x3000
	s_mov_b32 s24, 0xfffee000
	s_mov_b32 s25, 0xffff1000
	s_mov_b32 s30, 0xffff4000
	s_mov_b32 s31, 0xffff7000
	s_movk_i32 s33, 0xa000
	s_movk_i32 s34, 0xd000
	s_mov_b64 s[16:17], 0x18000
	v_mbcnt_hi_u32_b32 v1, -1, v196
	s_mov_b32 s35, s98
	s_branch .LBB0_10
